# attention tile loop: the per-tile K/V address step moved from four per-lane VALU adds to one 64-bit SALU step of the uniform base
# baseline (speedup 1.0000x reference)
; __device__ void attn_item(const Params& p, int s_idx, char* smem) {
;     ...
;     auto gload = [&](int kt, KV& st) {
; #pragma unroll
;         for (int i = 0; i < 2; ++i) {
;             const int c = tid + 256 * i, key = c >> 3, dc = c & 7;
;             const bf16_t* src = projb + (size_t)(kt * 64 + key) * NIN + h * 64 + dc * 8;
;             st.rk[i] = *(const u32x4*)(src + 512);
;             const int keyv = c & 63, dcv = c >> 6;
;             st.rv[i] = *(const u32x4*)(projb + (size_t)(kt * 64 + keyv) * NIN + 1024 + h * 64 + dcv * 8);
;         }
;         st.rkb = p.kb[(size_t)bh * S + kt * 64 + (tid & 63)];
;     ...
;             for (int kk = 0; kk < 4; ++kk) {
;                 const bf16x8 k0 = *(const bf16x8*)(sK + pr * 72 + kk * 16 + hh * 8);
;                 const bf16x8 k1 = *(const bf16x8*)(sK + (32 + pr) * 72 + kk * 16 + hh * 8);
;                 S0 = __builtin_amdgcn_mfma_f32_32x32x16_bf16(k0, qf[kk], S0, 0, 0, 0);
;                 S1 = __builtin_amdgcn_mfma_f32_32x32x16_bf16(k1, qf[kk], S1, 0, 0, 0);
;             }
;             float sv[32];
; #pragma unroll
;             for (int g = 0; g < 4; ++g) {
;                 const int kbase = (g >> 1) * 32 + (g & 1) * 16 + 8 * hh;
;                 const float4 b0 = *(const float4*)(sKb + kbase), b1 = *(const float4*)(sKb + kbase + 4);
;                 const int o = (g & 1) * 8;
;                 if (g >> 1) {
;                     sv[g * 8 + 0] = S1[o + 0] * sc + b0.x; sv[g * 8 + 1] = S1[o + 1] * sc + b0.y; sv[g * 8 + 2] = S1[o + 2] * sc + b0.z; sv[g * 8 + 3] = S1[o + 3] * sc + b0.w;
;                     sv[g * 8 + 4] = S1[o + 4] * sc + b1.x; sv[g * 8 + 5] = S1[o + 5] * sc + b1.y; sv[g * 8 + 6] = S1[o + 6] * sc + b1.z; sv[g * 8 + 7] = S1[o + 7] * sc + b1.w;
;                 } else {
;                     sv[g * 8 + 0] = S0[o + 0] * sc + b0.x; sv[g * 8 + 1] = S0[o + 1] * sc + b0.y; sv[g * 8 + 2] = S0[o + 2] * sc + b0.z; sv[g * 8 + 3] = S0[o + 3] * sc + b0.w;
;                     sv[g * 8 + 4] = S0[o + 4] * sc + b1.x; sv[g * 8 + 5] = S0[o + 5] * sc + b1.y; sv[g * 8 + 6] = S0[o + 6] * sc + b1.z; sv[g * 8 + 7] = S0[o + 7] * sc + b1.w;
;                 }
;             }
;             if (kt * 64 + 63 > wave_q0) {
; #pragma unroll
;                 for (int g = 0; g < 4; ++g) {
;                     const int kbase = kt * 64 + (g >> 1) * 32 + (g & 1) * 16 + 8 * hh;
; #pragma unroll
.LBB0_110:
	s_cmp_gt_u32 s16, 1
	s_cselect_b32 s32, 0x50400, 0
	global_load_dwordx4 v[92:95], v127, s[34:35] offset:1024
	global_load_dwordx4 v[84:87], v129, s[34:35] offset:2048
	global_load_dwordx4 v[88:91], v128, s[34:35] offset:1024
	global_load_dwordx4 v[80:83], v131, s[34:35] offset:2048
	s_sub_u32 s34, s34, s32
	s_subb_u32 s35, s35, 0
	v_lshl_add_u64 v[32:33], s[20:21], 2, v[104:105]
	global_load_dword v158, v[32:33], off offset:-256
	v_cmp_le_i32_e32 vcc, s16, v149
	s_and_saveexec_b64 s[36:37], vcc
	s_cbranch_execz .LBB0_114
	s_setprio 2
	ds_read_b128 v[32:35], v150 offset:4608
	ds_read_b128 v[36:39], v150
	ds_read_b128 v[116:119], v150 offset:32
	ds_read_b128 v[120:123], v150 offset:4640
	s_add_i32 s17, s20, 63
	v_cmp_gt_i32_e32 vcc, s17, v144
	s_waitcnt lgkmcnt(2)
	v_mfma_f32_32x32x16_bf16 v[48:63], v[36:39], v[64:67], 0
	v_mfma_f32_32x32x16_bf16 v[32:47], v[32:35], v[64:67], 0
	s_waitcnt lgkmcnt(1)
	v_mfma_f32_32x32x16_bf16 v[48:63], v[116:119], v[68:71], v[48:63]
	s_waitcnt lgkmcnt(0)
	v_mfma_f32_32x32x16_bf16 v[32:47], v[120:123], v[68:71], v[32:47]
	ds_read_b128 v[116:119], v150 offset:64
	ds_read_b128 v[120:123], v150 offset:4672
	s_waitcnt lgkmcnt(1)
	v_mfma_f32_32x32x16_bf16 v[48:63], v[116:119], v[72:75], v[48:63]
	s_waitcnt lgkmcnt(0)
	v_mfma_f32_32x32x16_bf16 v[32:47], v[120:123], v[72:75], v[32:47]
	ds_read_b128 v[116:119], v150 offset:96
	ds_read_b128 v[120:123], v150 offset:4704
	s_waitcnt lgkmcnt(1)
	v_mfma_f32_32x32x16_bf16 v[48:63], v[116:119], v[76:79], v[48:63]
	ds_read_b128 v[116:119], v151 offset:18432
	ds_read_b128 v[160:163], v151 offset:18448
	s_waitcnt lgkmcnt(2)
	v_mfma_f32_32x32x16_bf16 v[32:47], v[120:123], v[76:79], v[32:47]
	s_waitcnt lgkmcnt(1)
	s_nop 6
	v_fma_f32 v122, v48, s30, v116
	v_fma_f32 v123, v49, s30, v117
	v_fma_f32 v120, v50, s30, v118
	v_fma_f32 v121, v51, s30, v119
	ds_read_b128 v[48:51], v151 offset:18496
	s_waitcnt lgkmcnt(1)
	v_pk_fma_f32 v[118:119], v[52:53], s[30:31], v[160:161] op_sel_hi:[1,0,1]
	v_pk_fma_f32 v[54:55], v[54:55], s[30:31], v[162:163] op_sel_hi:[1,0,1]
	ds_read_b128 v[160:163], v151 offset:18560
	s_waitcnt lgkmcnt(1)
	v_pk_fma_f32 v[116:117], v[56:57], s[30:31], v[48:49] op_sel_hi:[1,0,1]
	v_pk_fma_f32 v[50:51], v[58:59], s[30:31], v[50:51] op_sel_hi:[1,0,1]
	ds_read_b128 v[56:59], v151 offset:18512
	s_waitcnt lgkmcnt(1)
	v_pk_fma_f32 v[52:53], v[34:35], s[30:31], v[162:163] op_sel_hi:[1,0,1]
	s_waitcnt lgkmcnt(0)
	v_pk_fma_f32 v[124:125], v[60:61], s[30:31], v[56:57] op_sel_hi:[1,0,1]
	v_pk_fma_f32 v[60:61], v[62:63], s[30:31], v[58:59] op_sel_hi:[1,0,1]
	v_pk_fma_f32 v[58:59], v[32:33], s[30:31], v[160:161] op_sel_hi:[1,0,1]
	ds_read_b128 v[32:35], v151 offset:18576
	s_waitcnt lgkmcnt(0)
	v_pk_fma_f32 v[56:57], v[36:37], s[30:31], v[32:33] op_sel_hi:[1,0,1]
	v_pk_fma_f32 v[48:49], v[38:39], s[30:31], v[34:35] op_sel_hi:[1,0,1]
	ds_read_b128 v[32:35], v151 offset:18624
	s_waitcnt lgkmcnt(0)
	v_pk_fma_f32 v[38:39], v[40:41], s[30:31], v[32:33] op_sel_hi:[1,0,1]
	v_pk_fma_f32 v[34:35], v[42:43], s[30:31], v[34:35] op_sel_hi:[1,0,1]
	ds_read_b128 v[40:43], v151 offset:18640
	s_waitcnt lgkmcnt(0)
	v_pk_fma_f32 v[36:37], v[44:45], s[30:31], v[40:41] op_sel_hi:[1,0,1]
	v_pk_fma_f32 v[32:33], v[46:47], s[30:31], v[42:43] op_sel_hi:[1,0,1]
	s_and_saveexec_b64 s[42:43], vcc
	s_cbranch_execz .LBB0_113
	v_add_u32_e32 v40, s20, v141
	v_cmp_ge_i32_e32 vcc, v99, v40
	v_or_b32_e32 v41, 3, v40
	v_or_b32_e32 v42, 2, v40
	v_cndmask_b32_e32 v122, v139, v122, vcc
	v_cmp_lt_i32_e32 vcc, v40, v99
	s_nop 1
	v_cndmask_b32_e32 v123, v139, v123, vcc
	v_cmp_le_i32_e32 vcc, v41, v97
	v_or_b32_e32 v41, 5, v40
	s_nop 0
	v_cndmask_b32_e32 v121, v139, v121, vcc
	v_cmp_le_i32_e32 vcc, v42, v98
	v_or_b32_e32 v42, 4, v40
	s_nop 0
	v_cndmask_b32_e32 v120, v139, v120, vcc
	v_cmp_le_i32_e32 vcc, v41, v97
	v_or_b32_e32 v41, 7, v40
	s_nop 0
	v_cndmask_b32_e32 v119, v139, v119, vcc
	v_cmp_le_i32_e32 vcc, v42, v98
	v_or_b32_e32 v42, 6, v40
	s_nop 0
	v_cndmask_b32_e32 v118, v139, v118, vcc
	v_cmp_le_i32_e32 vcc, v41, v97
	v_or_b32_e32 v41, 17, v40
	s_nop 0
	v_cndmask_b32_e32 v55, v139, v55, vcc
	v_cmp_le_i32_e32 vcc, v42, v98
	v_or_b32_e32 v42, 16, v40
	s_nop 0
	v_cndmask_b32_e32 v54, v139, v54, vcc
	v_cmp_le_i32_e32 vcc, v41, v97
	v_or_b32_e32 v41, 19, v40
	s_nop 0
	v_cndmask_b32_e32 v117, v139, v117, vcc
	v_cmp_le_i32_e32 vcc, v42, v98
	v_or_b32_e32 v42, 18, v40
	s_nop 0
	v_cndmask_b32_e32 v116, v139, v116, vcc
	v_cmp_le_i32_e32 vcc, v41, v97
	v_or_b32_e32 v41, 21, v40
	s_nop 0
	v_cndmask_b32_e32 v51, v139, v51, vcc
	v_cmp_le_i32_e32 vcc, v42, v98
	v_or_b32_e32 v42, 20, v40
	s_nop 0
	v_cndmask_b32_e32 v50, v139, v50, vcc
	v_cmp_le_i32_e32 vcc, v41, v97
	v_or_b32_e32 v41, 23, v40
	s_nop 0
	v_cndmask_b32_e32 v125, v139, v125, vcc
	v_cmp_le_i32_e32 vcc, v42, v98
	v_or_b32_e32 v42, 22, v40
	s_nop 0
	v_cndmask_b32_e32 v124, v139, v124, vcc
	v_cmp_le_i32_e32 vcc, v41, v97
	v_or_b32_e32 v41, 33, v40
	s_nop 0
	v_cndmask_b32_e32 v61, v139, v61, vcc
	v_cmp_le_i32_e32 vcc, v42, v98
	v_or_b32_e32 v42, 32, v40
	s_nop 0
	v_cndmask_b32_e32 v60, v139, v60, vcc
	v_cmp_le_i32_e32 vcc, v41, v97
	v_or_b32_e32 v41, 35, v40
	s_nop 0
	v_cndmask_b32_e32 v59, v139, v59, vcc
	v_cmp_le_i32_e32 vcc, v42, v98
	v_or_b32_e32 v42, 34, v40
	s_nop 0
	v_cndmask_b32_e32 v58, v139, v58, vcc
	v_cmp_le_i32_e32 vcc, v41, v97
	v_or_b32_e32 v41, 37, v40
	s_nop 0
	v_cndmask_b32_e32 v53, v139, v53, vcc
	v_cmp_le_i32_e32 vcc, v42, v98
	v_or_b32_e32 v42, 36, v40
	s_nop 0
	v_cndmask_b32_e32 v52, v139, v52, vcc
	v_cmp_le_i32_e32 vcc, v41, v97
	v_or_b32_e32 v41, 39, v40
	s_nop 0
	v_cndmask_b32_e32 v57, v139, v57, vcc
	v_cmp_le_i32_e32 vcc, v42, v98
	v_or_b32_e32 v42, 38, v40
	s_nop 0
	v_cndmask_b32_e32 v56, v139, v56, vcc
	v_cmp_le_i32_e32 vcc, v41, v97
	v_or_b32_e32 v41, 49, v40
	s_nop 0
	v_cndmask_b32_e32 v49, v139, v49, vcc
	v_cmp_le_i32_e32 vcc, v42, v98
	v_or_b32_e32 v42, 48, v40
	s_nop 0
	v_cndmask_b32_e32 v48, v139, v48, vcc
	v_cmp_le_i32_e32 vcc, v41, v97
	v_or_b32_e32 v41, 51, v40
	s_nop 0
	v_cndmask_b32_e32 v39, v139, v39, vcc
	v_cmp_le_i32_e32 vcc, v42, v98
	v_or_b32_e32 v42, 50, v40
	s_nop 0
	v_cndmask_b32_e32 v38, v139, v38, vcc
	v_cmp_le_i32_e32 vcc, v41, v97
	v_or_b32_e32 v41, 53, v40
	s_nop 0
	v_cndmask_b32_e32 v35, v139, v35, vcc
	v_cmp_le_i32_e32 vcc, v42, v98
	v_or_b32_e32 v42, 52, v40
	s_nop 0
	v_cndmask_b32_e32 v34, v139, v34, vcc
	v_cmp_le_i32_e32 vcc, v41, v97
	v_or_b32_e32 v41, 55, v40
	v_or_b32_e32 v40, 54, v40
	v_cndmask_b32_e32 v37, v139, v37, vcc
	v_cmp_le_i32_e32 vcc, v42, v98
	s_nop 1
	v_cndmask_b32_e32 v36, v139, v36, vcc
	v_cmp_le_i32_e32 vcc, v41, v97
	s_nop 1
	v_cndmask_b32_e32 v33, v139, v33, vcc
	v_cmp_le_i32_e32 vcc, v40, v98
	s_nop 1
	v_cndmask_b32_e32 v32, v139, v32, vcc

; __device__ void attn_item(const Params& p, int s_idx, char* smem) {
;     ...
;             for (int kk = 0; kk < 4; ++kk) {
;                 const bf16x8 k0 = *(const bf16x8*)(sK + pr * 72 + kk * 16 + hh * 8);
;                 const bf16x8 k1 = *(const bf16x8*)(sK + (32 + pr) * 72 + kk * 16 + hh * 8);
;                 S0 = __builtin_amdgcn_mfma_f32_32x32x16_bf16(k0, qf[kk], S0, 0, 0, 0);
;                 S1 = __builtin_amdgcn_mfma_f32_32x32x16_bf16(k1, qf[kk], S1, 0, 0, 0);
;             }
;             float sv[32];
; #pragma unroll
;             for (int g = 0; g < 4; ++g) {
;                 const int kbase = (g >> 1) * 32 + (g & 1) * 16 + 8 * hh;
;                 const float4 b0 = *(const float4*)(sKb + kbase), b1 = *(const float4*)(sKb + kbase + 4);
;                 const int o = (g & 1) * 8;
;                 if (g >> 1) {
;                     sv[g * 8 + 0] = S1[o + 0] * sc + b0.x; sv[g * 8 + 1] = S1[o + 1] * sc + b0.y; sv[g * 8 + 2] = S1[o + 2] * sc + b0.z; sv[g * 8 + 3] = S1[o + 3] * sc + b0.w;
;                     sv[g * 8 + 4] = S1[o + 4] * sc + b1.x; sv[g * 8 + 5] = S1[o + 5] * sc + b1.y; sv[g * 8 + 6] = S1[o + 6] * sc + b1.z; sv[g * 8 + 7] = S1[o + 7] * sc + b1.w;
;                 } else {
;                     sv[g * 8 + 0] = S0[o + 0] * sc + b0.x; sv[g * 8 + 1] = S0[o + 1] * sc + b0.y; sv[g * 8 + 2] = S0[o + 2] * sc + b0.z; sv[g * 8 + 3] = S0[o + 3] * sc + b0.w;
;                     sv[g * 8 + 4] = S0[o + 4] * sc + b1.x; sv[g * 8 + 5] = S0[o + 5] * sc + b1.y; sv[g * 8 + 6] = S0[o + 6] * sc + b1.z; sv[g * 8 + 7] = S0[o + 7] * sc + b1.w;
;                 }
;             }
;             if (kt * 64 + 63 > wave_q0) {
; #pragma unroll
;                 for (int g = 0; g < 4; ++g) {
;                     const int kbase = kt * 64 + (g >> 1) * 32 + (g & 1) * 16 + 8 * hh;
; #pragma unroll
;                     for (int e = 0; e < 8; ++e) if (kbase + e > qrow) sv[g * 8 + e] = -INFINITY;
;                 }
;             }
;     ...
;         __syncthreads();
;         gload(min(kt + 2, nkt - 1), sa);
;         compute(kt + 1, 1);
.LBB0_116:
	s_or_b64 exec, exec, s[24:25]
	s_add_i32 s17, s16, -2
	s_max_i32 s18, s17, 0
	s_lshl_b32 s18, s18, 6
	s_waitcnt lgkmcnt(0)
	s_barrier
	global_load_dwordx4 v[92:95], v127, s[34:35] offset:1024
	global_load_dwordx4 v[84:87], v129, s[34:35] offset:2048
	s_mov_b32 s19, s21
	global_load_dwordx4 v[88:91], v128, s[34:35] offset:1024
	global_load_dwordx4 v[80:83], v131, s[34:35] offset:2048
	s_sub_u32 s34, s34, s32
	s_subb_u32 s35, s35, 0
	v_lshl_add_u64 v[32:33], s[18:19], 2, v[104:105]
	global_load_dword v158, v[32:33], off
	v_cmp_lt_i32_e32 vcc, s17, v149
	s_and_saveexec_b64 s[36:37], vcc
	s_cbranch_execz .LBB0_120
	s_setprio 2
	ds_read_b128 v[32:35], v150 offset:23296
	ds_read_b128 v[36:39], v150 offset:18688
	ds_read_b128 v[116:119], v150 offset:18720
	ds_read_b128 v[120:123], v150 offset:23328
	s_add_i32 s18, s20, -1
	v_cmp_gt_i32_e32 vcc, s18, v144
	s_waitcnt lgkmcnt(2)
	v_mfma_f32_32x32x16_bf16 v[48:63], v[36:39], v[64:67], 0
	v_mfma_f32_32x32x16_bf16 v[32:47], v[32:35], v[64:67], 0
	s_waitcnt lgkmcnt(1)
	v_mfma_f32_32x32x16_bf16 v[48:63], v[116:119], v[68:71], v[48:63]
	s_waitcnt lgkmcnt(0)
	v_mfma_f32_32x32x16_bf16 v[32:47], v[120:123], v[68:71], v[32:47]
	ds_read_b128 v[116:119], v150 offset:18752
	ds_read_b128 v[120:123], v150 offset:23360
	s_waitcnt lgkmcnt(1)
	v_mfma_f32_32x32x16_bf16 v[48:63], v[116:119], v[72:75], v[48:63]
	s_waitcnt lgkmcnt(0)
	v_mfma_f32_32x32x16_bf16 v[32:47], v[120:123], v[72:75], v[32:47]
	ds_read_b128 v[116:119], v150 offset:18784
	ds_read_b128 v[120:123], v150 offset:23392
	s_waitcnt lgkmcnt(1)
	v_mfma_f32_32x32x16_bf16 v[48:63], v[116:119], v[76:79], v[48:63]
	ds_read_b128 v[116:119], v151 offset:37120
	ds_read_b128 v[160:163], v151 offset:37136
	s_waitcnt lgkmcnt(2)
	v_mfma_f32_32x32x16_bf16 v[32:47], v[120:123], v[76:79], v[32:47]
	s_waitcnt lgkmcnt(1)
	s_nop 6
	v_fma_f32 v122, v48, s30, v116
	v_fma_f32 v123, v49, s30, v117
	v_fma_f32 v120, v50, s30, v118
	v_fma_f32 v121, v51, s30, v119
	ds_read_b128 v[48:51], v151 offset:37184
	s_waitcnt lgkmcnt(1)
	v_pk_fma_f32 v[118:119], v[52:53], s[30:31], v[160:161] op_sel_hi:[1,0,1]
	v_pk_fma_f32 v[54:55], v[54:55], s[30:31], v[162:163] op_sel_hi:[1,0,1]
	ds_read_b128 v[160:163], v151 offset:37248
	s_waitcnt lgkmcnt(1)
	v_pk_fma_f32 v[116:117], v[56:57], s[30:31], v[48:49] op_sel_hi:[1,0,1]
	v_pk_fma_f32 v[50:51], v[58:59], s[30:31], v[50:51] op_sel_hi:[1,0,1]
	ds_read_b128 v[56:59], v151 offset:37200
	s_waitcnt lgkmcnt(1)
	v_pk_fma_f32 v[52:53], v[34:35], s[30:31], v[162:163] op_sel_hi:[1,0,1]
	s_waitcnt lgkmcnt(0)
	v_pk_fma_f32 v[124:125], v[60:61], s[30:31], v[56:57] op_sel_hi:[1,0,1]
	v_pk_fma_f32 v[60:61], v[62:63], s[30:31], v[58:59] op_sel_hi:[1,0,1]
	v_pk_fma_f32 v[58:59], v[32:33], s[30:31], v[160:161] op_sel_hi:[1,0,1]
	ds_read_b128 v[32:35], v151 offset:37264
	s_waitcnt lgkmcnt(0)
	v_pk_fma_f32 v[56:57], v[36:37], s[30:31], v[32:33] op_sel_hi:[1,0,1]
	v_pk_fma_f32 v[48:49], v[38:39], s[30:31], v[34:35] op_sel_hi:[1,0,1]
	ds_read_b128 v[32:35], v151 offset:37312
	s_waitcnt lgkmcnt(0)
	v_pk_fma_f32 v[38:39], v[40:41], s[30:31], v[32:33] op_sel_hi:[1,0,1]
	v_pk_fma_f32 v[34:35], v[42:43], s[30:31], v[34:35] op_sel_hi:[1,0,1]
	ds_read_b128 v[40:43], v151 offset:37328
	s_waitcnt lgkmcnt(0)
	v_pk_fma_f32 v[36:37], v[44:45], s[30:31], v[40:41] op_sel_hi:[1,0,1]
	v_pk_fma_f32 v[32:33], v[46:47], s[30:31], v[42:43] op_sel_hi:[1,0,1]
	s_and_saveexec_b64 s[42:43], vcc
	s_cbranch_execz .LBB0_119
	s_add_i32 s19, s20, 0xffffffc0
	v_add_u32_e32 v40, s19, v141
	v_cmp_ge_i32_e32 vcc, v99, v40
	v_or_b32_e32 v41, 3, v40
	v_or_b32_e32 v42, 2, v40
	v_cndmask_b32_e32 v122, v139, v122, vcc
	v_cmp_lt_i32_e32 vcc, v40, v99
	s_nop 1
	v_cndmask_b32_e32 v123, v139, v123, vcc
	v_cmp_le_i32_e32 vcc, v41, v97
	v_or_b32_e32 v41, 5, v40
	s_nop 0
	v_cndmask_b32_e32 v121, v139, v121, vcc
	v_cmp_le_i32_e32 vcc, v42, v98
	v_or_b32_e32 v42, 4, v40
	s_nop 0
	v_cndmask_b32_e32 v120, v139, v120, vcc
	v_cmp_le_i32_e32 vcc, v41, v97
	v_or_b32_e32 v41, 7, v40
	s_nop 0
	v_cndmask_b32_e32 v119, v139, v119, vcc
	v_cmp_le_i32_e32 vcc, v42, v98
	v_or_b32_e32 v42, 6, v40
	s_nop 0
	v_cndmask_b32_e32 v118, v139, v118, vcc
	v_cmp_le_i32_e32 vcc, v41, v97
	v_or_b32_e32 v41, 17, v40
	s_nop 0
	v_cndmask_b32_e32 v55, v139, v55, vcc
	v_cmp_le_i32_e32 vcc, v42, v98
	v_or_b32_e32 v42, 16, v40
	s_nop 0
	v_cndmask_b32_e32 v54, v139, v54, vcc
	v_cmp_le_i32_e32 vcc, v41, v97
	v_or_b32_e32 v41, 19, v40
	s_nop 0
	v_cndmask_b32_e32 v117, v139, v117, vcc
	v_cmp_le_i32_e32 vcc, v42, v98
	v_or_b32_e32 v42, 18, v40
	s_nop 0
	v_cndmask_b32_e32 v116, v139, v116, vcc
	v_cmp_le_i32_e32 vcc, v41, v97
	v_or_b32_e32 v41, 21, v40
	s_nop 0
	v_cndmask_b32_e32 v51, v139, v51, vcc
	v_cmp_le_i32_e32 vcc, v42, v98
	v_or_b32_e32 v42, 20, v40
	s_nop 0
	v_cndmask_b32_e32 v50, v139, v50, vcc
	v_cmp_le_i32_e32 vcc, v41, v97
	v_or_b32_e32 v41, 23, v40
	s_nop 0
	v_cndmask_b32_e32 v125, v139, v125, vcc
	v_cmp_le_i32_e32 vcc, v42, v98
	v_or_b32_e32 v42, 22, v40
	s_nop 0
	v_cndmask_b32_e32 v124, v139, v124, vcc
	v_cmp_le_i32_e32 vcc, v41, v97
	v_or_b32_e32 v41, 33, v40
	s_nop 0
	v_cndmask_b32_e32 v61, v139, v61, vcc
	v_cmp_le_i32_e32 vcc, v42, v98
	v_or_b32_e32 v42, 32, v40
	s_nop 0
	v_cndmask_b32_e32 v60, v139, v60, vcc
	v_cmp_le_i32_e32 vcc, v41, v97
	v_or_b32_e32 v41, 35, v40
	s_nop 0
	v_cndmask_b32_e32 v59, v139, v59, vcc
	v_cmp_le_i32_e32 vcc, v42, v98
	v_or_b32_e32 v42, 34, v40
	s_nop 0
	v_cndmask_b32_e32 v58, v139, v58, vcc
	v_cmp_le_i32_e32 vcc, v41, v97
	v_or_b32_e32 v41, 37, v40
	s_nop 0
	v_cndmask_b32_e32 v53, v139, v53, vcc
	v_cmp_le_i32_e32 vcc, v42, v98
	v_or_b32_e32 v42, 36, v40
	s_nop 0
	v_cndmask_b32_e32 v52, v139, v52, vcc
	v_cmp_le_i32_e32 vcc, v41, v97
	v_or_b32_e32 v41, 39, v40
	s_nop 0
	v_cndmask_b32_e32 v57, v139, v57, vcc
	v_cmp_le_i32_e32 vcc, v42, v98
	v_or_b32_e32 v42, 38, v40
	s_nop 0
	v_cndmask_b32_e32 v56, v139, v56, vcc
	v_cmp_le_i32_e32 vcc, v41, v97
	v_or_b32_e32 v41, 49, v40
	s_nop 0
	v_cndmask_b32_e32 v49, v139, v49, vcc
	v_cmp_le_i32_e32 vcc, v42, v98
	v_or_b32_e32 v42, 48, v40
	s_nop 0
	v_cndmask_b32_e32 v48, v139, v48, vcc
	v_cmp_le_i32_e32 vcc, v41, v97
	v_or_b32_e32 v41, 51, v40
	s_nop 0
	v_cndmask_b32_e32 v39, v139, v39, vcc
	v_cmp_le_i32_e32 vcc, v42, v98
	v_or_b32_e32 v42, 50, v40
	s_nop 0
	v_cndmask_b32_e32 v38, v139, v38, vcc
	v_cmp_le_i32_e32 vcc, v41, v97
	v_or_b32_e32 v41, 53, v40
	s_nop 0
	v_cndmask_b32_e32 v35, v139, v35, vcc
	v_cmp_le_i32_e32 vcc, v42, v98
	v_or_b32_e32 v42, 52, v40
	s_nop 0
	v_cndmask_b32_e32 v34, v139, v34, vcc
	v_cmp_le_i32_e32 vcc, v41, v97
	v_or_b32_e32 v41, 55, v40
	v_or_b32_e32 v40, 54, v40
	v_cndmask_b32_e32 v37, v139, v37, vcc
	v_cmp_le_i32_e32 vcc, v42, v98
	s_nop 1
	v_cndmask_b32_e32 v36, v139, v36, vcc
	v_cmp_le_i32_e32 vcc, v41, v97
	s_nop 1
	v_cndmask_b32_e32 v33, v139, v33, vcc
	v_cmp_le_i32_e32 vcc, v40, v98
	s_nop 1
	v_cndmask_b32_e32 v32, v139, v32, vcc
